# GQA job: one static s_setprio 1 for waves 4-7 at job entry, per-cluster priority flips removed (reset at the job-queue header)
# speedup vs baseline: 1.0063x; 1.0054x over previous
; __device__ void mixer_phase(const Params& p, int layer, char* smem) {
;     ...
;   for (;;) {
;     if (threadIdx.x == 0) *slot = atomicAdd(ctr, 1u);
.LBB0_433:
	s_setprio 0
	s_and_saveexec_b64 s[0:1], s[38:39]
	s_cbranch_execz .LBB0_437
	s_mov_b64 s[4:5], exec
	v_mbcnt_lo_u32_b32 v0, s4, 0
	v_mbcnt_hi_u32_b32 v0, s5, v0
	v_cmp_eq_u32_e32 vcc, 0, v0
	s_and_saveexec_b64 s[2:3], vcc
	s_cbranch_execz .LBB0_436
	s_bcnt1_i32_b64 s4, s[4:5]
	s_waitcnt vmcnt(11)
	v_mov_b32_e32 v2, s4
	v_readlane_b32 s4, v255, 3
	v_readlane_b32 s5, v255, 4
	s_nop 4
	global_atomic_add v2, v1, v2, s[4:5] sc0

; template <int kind>
; __device__ void attn_job(const Params& p, int layer, int idx, char* smem) {
;     ...
;     b = idx >> 5; const int kvh = (idx >> 4) & 1, qt = idx & 15;
;     const int head = kvh * 2 + (w >> 2);
;     qtok = b * SEQ + qt * 128 + (w & 3) * 32 + tq; qcol = GQ + head * 64; ocol = 512 + head * 64;
;     kcol = GK + kvh * 64; vcol = GV + kvh * 64; nlat = 32; lat0 = b * SEQ;
;   } else if (kind == 1) {
;     b = idx >> 5; hN = (idx >> 3) & 3; const int rg = idx & 7;
;     const int rA = rg * 4 + 2 * (w >> 2), cb = w & 3;
;     qrow_l = rA + (tq >> 4); qc = 16 * cb + (tq & 15);
;     qtok = b * SEQ + qrow_l * 64 + qc; qcol = NQ + hN * 64; ocol = 768 + hN * 64;
;     kcol = NK + hN * 64; vcol = NV + hN * 64;
;     R0 = min(max(rg * 4 - 4, 0), 24);
;     const int R1 = min(max(rg * 4 + 3 - 4, 0), 24) + 8;
;     nlat = R1 - R0; lat0 = b * SEQ + R0 * 64;
;     k0 = min(max(16 * cb - 8, 0), 32);
;     r0A = min(max(rA - 4, 0), 24);
;     r0l = min(max(qrow_l - 4, 0), 24);
;   } else if (kind == 2) {
;     b = idx >> 2; const int kvh = (idx >> 1) & 1, half = idx & 1;
;     const int head = kvh * 2 + (w >> 2);
;     qtok = NLAT + b * CTXL + half * 128 + (w & 3) * 32 + tq; qcol = GQ + head * 64; ocol = 512 + head * 64;
;     kcol = GK + kvh * 64; vcol = GV + kvh * 64;
;   } else {
;     b = idx >> 2; hN = idx & 3;
;     qtok = NLAT + b * CTXL + w * 32 + tq; qcol = NQ + hN * 64; ocol = 768 + hN * 64;
;     kcol = NK + hN * 64; vcol = NV + hN * 64;
;   }
;   const int ntiles = 4 + nlat;
;   const u16* Z = p.z;
;   if (kind == 1) {
;     for (int i = tid; i < 16 + 15 * 32 + 32; i += NTHR) {
;       const int j = i - 16, rr = j >> 5, cc = j & 31;
;       rpbs[i] = (j >= 0 && rr < 15 && cc < 31) ? p.rpb[((size_t)(layer * 4 + hN) * 15 + rr) * 31 + cc] : 0.f;
;     }
;   }
;   bf16x8 qf[4];
; #pragma unroll
;   for (int st = 0; st < 4; ++st) qf[st] = *(const bf16x8*)(Z + (size_t)qtok * ZW + qcol + 16 * st + 8 * hh);
;   unsigned colmask = 0;
;   int dcbase = 0;
;   if (kind == 1) {
;     const int cs = min(max(qc - 8, 0), 48);
; #pragma unroll
;     for (int e = 0; e < 16; ++e) {
;       const int kc = k0 + (e & 3) + 8 * (e >> 2) + 4 * hh;
;       colmask |= ((kc >= cs) && (kc < cs + 16)) ? (1u << e) : 0u;
;     }
;     dcbase = 16 + k0 + 4 * hh - qc + 15;
;   }
;   float mrun = -1e30f, lsum = 0.f;
;   f32x16 O[2], zero16;
; #pragma unroll
.LBB0_518:
	s_andn2_b64 vcc, exec, s[0:1]
	s_cbranch_vccnz .LBB0_529
	v_readfirstlane_b32 s100, v234
	s_nop 0
	s_bitcmp1_b32 s100, 8
	s_cbranch_scc0 .Lgqa_prio_skip
	s_setprio 1
.Lgqa_prio_skip:
	s_add_i32 s0, s18, 0xffffff00
	s_lshr_b32 s1, s0, 5
	s_bfe_u32 s2, s18, 0x10004
	v_mov_b32_e32 v22, v234
	s_lshl_b32 s4, s1, 11
	s_lshl_b32 s3, s2, 6
	s_lshl_b32 s5, s1, 8
	s_lshl_b32 s1, s2, 7
	s_lshl_b32 s0, s0, 7
	v_readfirstlane_b32 s2, v22
	s_lshr_b32 s6, s2, 1
	s_and_b32 s0, s0, 0x780
	s_and_b32 s6, s6, 0x60
	s_or_b32 s0, s0, s6
	v_and_b32_e32 v23, 31, v22
	s_or_b32 s0, s0, s4
	s_waitcnt vmcnt(5)
	v_or_b32_e32 v139, s0, v23
	s_ashr_i32 s0, s2, 2
	s_andn2_b32 s0, s0, 63
	s_add_i32 s0, s0, s1
	s_movk_i32 s1, 0xe00
	v_mul_lo_u32 v0, v139, s1
	v_bfe_u32 v24, v22, 5, 1
	v_lshl_add_u64 v[2:3], v[0:1], 1, s[80:81]
	s_ashr_i32 s1, s0, 31
	s_or_b32 s7, s3, 0xa00
	s_or_b32 s8, s3, 0xa80
	s_add_i32 s3, s5, 0x8000
	v_lshl_add_u64 v[2:3], s[0:1], 1, v[2:3]
	s_waitcnt vmcnt(4)
	v_lshlrev_b32_e32 v140, 4, v24
	v_mov_b32_e32 v141, v1
	v_ashrrev_i32_e32 v25, 3, v22
	v_mov_b64_e32 v[16:17], s[80:81]
	v_lshl_add_u64 v[2:3], v[2:3], 0, v[140:141]
	s_mov_b64 s[10:11], 0x1200
	s_movk_i32 s2, 0x1000
	v_add_u32_e32 v18, s3, v25
	v_lshl_add_u64 v[4:5], v[2:3], 0, s[10:11]
	v_add_co_u32_e32 v2, vcc, s2, v2
	v_mad_i64_i32 v[16:17], s[2:3], v18, s79, v[16:17]
	v_readlane_b32 s2, v254, 34
	v_lshlrev_b32_e32 v20, 3, v22
	v_addc_co_u32_e32 v3, vcc, 0, v3, vcc
	v_mov_b32_e32 v14, v1
	v_mov_b32_e32 v15, v1
	v_readlane_b32 s3, v254, 35
	s_lshl_b32 s2, s7, 1
	v_and_b32_e32 v142, 56, v20
	global_load_dwordx4 v[90:93], v[4:5], off offset:32
	global_load_dwordx4 v[86:89], v[4:5], off offset:64
	global_load_dwordx4 v[94:97], v[2:3], off offset:512
	global_load_dwordx4 v[82:85], v[4:5], off offset:96
	v_mov_b32_e32 v0, v1
	v_mov_b32_e32 v2, v1
	v_mov_b32_e32 v3, v1
	v_mov_b32_e32 v4, v1
	v_mov_b32_e32 v5, v1
	v_mov_b32_e32 v6, v1
	v_mov_b32_e32 v7, v1
	v_mov_b32_e32 v8, v1
	v_mov_b32_e32 v9, v1
	v_mov_b32_e32 v10, v1
	v_mov_b32_e32 v11, v1
	v_mov_b32_e32 v12, v1
	v_mov_b32_e32 v13, v1
	v_mov_b64_e32 v[48:49], v[14:15]
	v_lshl_add_u64 v[18:19], v[16:17], 0, s[2:3]
	v_lshlrev_b32_e32 v20, 1, v142
	v_mov_b32_e32 v21, v1
	s_lshl_b32 s2, s8, 1
	v_mov_b64_e32 v[46:47], v[12:13]
	v_mov_b64_e32 v[44:45], v[10:11]
	v_mov_b64_e32 v[42:43], v[8:9]
	v_mov_b64_e32 v[40:41], v[6:7]
	v_mov_b64_e32 v[38:39], v[4:5]
	v_mov_b64_e32 v[36:37], v[2:3]
	v_mov_b64_e32 v[34:35], v[0:1]
	v_lshl_add_u64 v[18:19], v[18:19], 0, v[20:21]
	v_lshl_add_u64 v[16:17], v[16:17], 0, s[2:3]
	v_lshl_add_u64 v[16:17], v[16:17], 0, v[20:21]
	global_load_dwordx4 v[98:101], v[18:19], off
	global_load_dwordx4 v[102:105], v[16:17], off
	v_and_b32_e32 v17, 16, v22
	v_lshlrev_b32_e32 v18, 2, v22
	v_bfe_u32 v16, v22, 2, 2
	v_and_or_b32 v17, v18, 12, v17
	v_lshl_or_b32 v16, v24, 2, v16
	v_lshlrev_b32_e32 v17, 1, v17
	s_movk_i32 s2, 0x90
	v_mad_u32_u24 v141, v16, s2, v17
	s_movk_i32 s2, 0x48
	v_lshlrev_b32_e32 v138, 3, v24
	v_mul_lo_u32 v16, v25, s2
	v_mul_u32_u24_e32 v143, 0x90, v23
	v_add_u32_e32 v147, 64, v25
	s_lshl_b32 s2, s7, 1
	v_mov_b64_e32 v[32:33], v[14:15]
	v_writelane_b32 v254, s2, 34
	v_lshlrev_b32_e32 v148, 1, v16
	v_mov_b64_e32 v[30:31], v[12:13]
	v_mov_b64_e32 v[28:29], v[10:11]
	v_mov_b64_e32 v[26:27], v[8:9]
	v_mov_b64_e32 v[24:25], v[6:7]
	v_mov_b64_e32 v[22:23], v[4:5]
	v_mov_b64_e32 v[20:21], v[2:3]
	v_mov_b64_e32 v[18:19], v[0:1]
	v_mov_b64_e32 v[16:17], v[14:15]
	s_mov_b32 s6, 0
	v_mov_b32_e32 v149, 0
	v_mov_b32_e32 v145, 0xf149f2ca
	v_writelane_b32 v254, s3, 35
	s_lshl_b32 s2, s8, 1
	s_mov_b32 s7, 0
	v_mov_b64_e32 v[14:15], v[12:13]
	v_mov_b64_e32 v[12:13], v[10:11]
	v_mov_b64_e32 v[10:11], v[8:9]
	v_mov_b64_e32 v[8:9], v[6:7]
	v_mov_b64_e32 v[6:7], v[4:5]
	v_mov_b64_e32 v[4:5], v[2:3]
	v_mov_b64_e32 v[2:3], v[0:1]
; template <int NB>
; DI void softmax_pv(f32x16 (&s)[2], float& mrun, float& lsum, f32x16 (&O)[2], unsigned vaddr) {
;     ...
;   float mx = -1e30f;
; #pragma unroll
;   for (int kb = 0; kb < NB; ++kb)
; #pragma unroll
;     for (int e = 0; e < 16; ++e) mx = fmaxf(mx, s[kb][e]);
;   mx = xmax32(mx);
;   constexpr float THR = 8.f;
;   float alpha = 1.f;
;   if (__builtin_amdgcn_ballot_w64(mx - mrun > THR) != 0ull) {
;     const float mnew = fmaxf(mrun, mx);
;     alpha = __builtin_amdgcn_exp2f((mrun - mnew) * L2E);
;     mrun = mnew;
; #pragma unroll
; template <int kind>
; __device__ void attn_job(const Params& p, int layer, int idx, char* smem) {
;     ...
;   for (int i = 0; i < ntiles; ++i) {
;     u16* Kb = Ks + (i & 1) * 64 * KS_STRIDE;
;     u16* Vb = Vt + (i & 1) * 64 * KS_STRIDE;
;     *(u32x4*)(Kb + lkey * KS_STRIDE + lc * 8) = kreg;
;     *(u32x4*)(Vb + lkey * KS_STRIDE + lc * 8) = vreg;
;     lds_barrier();
;     if (i + 1 < ntiles) {
;       const size_t ro = (size_t)(tile_row0(i + 1) + lkey) * ZW;
;       kreg = *(const u32x4*)(Z + ro + kcol + lc * 8);
;       vreg = *(const u32x4*)(Z + ro + vcol + lc * 8);
;     }
;     if (kind == 1 && i >= 4) {
;       const int kr = R0 + i - 4;
;       if (kr >= r0A && kr < r0A + 9) {
;         f32x16 s[2];
; #pragma unroll
;         for (int st = 0; st < 4; ++st) s[0] = mfma32(ld_frag16(Kb + (k0 + tq) * KS_STRIDE + 16 * st + 8 * hh), qf[st], st == 0 ? zero16 : s[0]);
;         const bool rowvalid = (kr >= r0l) && (kr < r0l + 8);
;         const unsigned m = rowvalid ? colmask : 0u;
;         const float* brow = rpbs + (kr - qrow_l + 7) * 32 + dcbase;
; #pragma unroll
;         for (int e = 0; e < 16; ++e) {
;           const float bias = brow[(e & 3) + 8 * (e >> 2)];
;           s[0][e] = ((m >> e) & 1u) ? s[0][e] + bias : -1e30f;
;         }
;         softmax_pv<1>(s, mrun, lsum, O, (unsigned)(size_t)Vb + vlane_off + (unsigned)(k0 * KS_STRIDE * 2));
;       }
;     } else {
;       f32x16 s[2];
;       __builtin_amdgcn_s_setprio(1);
; #pragma unroll
;       for (int kb = 0; kb < 2; ++kb) {
; #pragma unroll
;         for (int st = 0; st < 4; ++st) s[kb] = mfma32(ld_frag16(Kb + (kb * 32 + tq) * KS_STRIDE + 16 * st + 8 * hh), qf[st], st == 0 ? zero16 : s[kb]);
;       }
;       __builtin_amdgcn_s_setprio(0);
;       softmax_pv<2>(s, mrun, lsum, O, (unsigned)(size_t)Vb + vlane_off);
.LBB0_520:
	s_and_b32 s3, s6, 64
	s_mulk_i32 s3, 0x90
	s_add_i32 s10, s3, 0
	s_add_i32 s11, s10, 0x4800
	s_cmp_lt_u32 s7, 3
	s_cselect_b32 s3, 0x8000, s26
	s_cselect_b32 s8, s5, s4
	v_lshlrev_b32_e32 v0, 1, v142
	s_add_i32 s3, s8, s3
	v_add3_u32 v50, s10, v148, v0
	s_add_i32 s3, s3, s6
	s_waitcnt vmcnt(1)
	ds_write_b128 v50, v[98:101]
	s_waitcnt vmcnt(0)
	ds_write_b128 v50, v[102:105] offset:18432
	v_add_u32_e32 v52, s3, v147
	v_mov_b64_e32 v[50:51], s[80:81]
	v_mad_i64_i32 v[50:51], s[8:9], v52, s79, v[50:51]
	v_readlane_b32 s8, v254, 34
	v_readlane_b32 s9, v254, 35
	s_mov_b32 s3, s9
	s_waitcnt lgkmcnt(0)
	s_barrier
	v_lshl_add_u64 v[52:53], v[50:51], 0, s[8:9]
	v_lshl_add_u64 v[52:53], v[52:53], 0, v[0:1]
	v_lshl_add_u64 v[50:51], v[50:51], 0, s[2:3]
	v_lshl_add_u64 v[50:51], v[50:51], 0, v[0:1]
	global_load_dwordx4 v[98:101], v[52:53], off
	global_load_dwordx4 v[102:105], v[50:51], off
	s_nop 0
	v_add3_u32 v110, s10, v140, v143
	v_add_u32_e32 v144, s11, v141
	ds_read_b128 v[178:181], v110
	ds_read_b128 v[182:185], v110 offset:32
	ds_read_b128 v[186:189], v110 offset:64
	ds_read_b128 v[190:193], v110 offset:96
	ds_read_b128 v[194:197], v110 offset:4608
	ds_read_b128 v[198:201], v110 offset:4640
	ds_read_b128 v[202:205], v110 offset:4672
	ds_read_b128 v[206:209], v110 offset:4704
	ds_read_b64_tr_b16 v[134:135], v144 offset:0
	ds_read_b64_tr_b16 v[136:137], v144 offset:1152
	ds_read_b64_tr_b16 v[130:131], v144 offset:64
	ds_read_b64_tr_b16 v[132:133], v144 offset:1216
	s_waitcnt lgkmcnt(11)
	v_mfma_f32_32x32x16_bf16 v[66:81], v[178:181], v[94:97], v[34:49]
	ds_read_b64_tr_b16 v[126:127], v144 offset:2304
	s_waitcnt lgkmcnt(11)
	v_mfma_f32_32x32x16_bf16 v[66:81], v[182:185], v[90:93], v[66:81]
	ds_read_b64_tr_b16 v[128:129], v144 offset:3456
	s_waitcnt lgkmcnt(11)
	v_mfma_f32_32x32x16_bf16 v[66:81], v[186:189], v[86:89], v[66:81]
	ds_read_b64_tr_b16 v[122:123], v144 offset:2368
	s_waitcnt lgkmcnt(11)
	v_mfma_f32_32x32x16_bf16 v[66:81], v[190:193], v[82:85], v[66:81]
	ds_read_b64_tr_b16 v[124:125], v144 offset:3520
	s_waitcnt lgkmcnt(11)
	v_mfma_f32_32x32x16_bf16 v[50:65], v[194:197], v[94:97], v[34:49]
	ds_read_b64_tr_b16 v[118:119], v144 offset:4608
	s_waitcnt lgkmcnt(11)
	v_mfma_f32_32x32x16_bf16 v[50:65], v[198:201], v[90:93], v[50:65]
	ds_read_b64_tr_b16 v[120:121], v144 offset:5760
	s_waitcnt lgkmcnt(11)
	v_mfma_f32_32x32x16_bf16 v[50:65], v[202:205], v[86:89], v[50:65]
	ds_read_b64_tr_b16 v[114:115], v144 offset:4672
	s_waitcnt lgkmcnt(11)
	v_mfma_f32_32x32x16_bf16 v[50:65], v[206:209], v[82:85], v[50:65]
	ds_read_b64_tr_b16 v[116:117], v144 offset:5824
	ds_read_b64_tr_b16 v[110:111], v144 offset:6912
	ds_read_b64_tr_b16 v[112:113], v144 offset:8064
	ds_read_b64_tr_b16 v[106:107], v144 offset:6976
	ds_read_b64_tr_b16 v[108:109], v144 offset:8128
	s_nop 0
	v_max3_f32 v144, v66, s24, v67
	v_max3_f32 v144, v144, v68, v69
	v_max3_f32 v144, v144, v70, v71
	v_max3_f32 v144, v144, v72, v73
	v_max3_f32 v144, v144, v74, v75
	v_max3_f32 v144, v144, v76, v77
	v_max3_f32 v144, v144, v78, v79
	v_max3_f32 v144, v144, v80, v81
	s_nop 1
	v_max3_f32 v144, v144, v50, v51
	v_max3_f32 v144, v144, v52, v53
	v_max3_f32 v144, v144, v54, v55
	v_max3_f32 v144, v144, v56, v57
	v_max3_f32 v144, v144, v58, v59
	v_max3_f32 v144, v144, v60, v61
	v_max3_f32 v144, v144, v62, v63
	v_max3_f32 v144, v144, v64, v65
	v_mov_b32_e32 v146, v144
	s_nop 1
	v_permlane32_swap_b32_e32 v144, v146
	v_max_f32_e32 v146, v146, v146
	v_max_f32_e32 v144, v144, v144
	v_max_f32_e32 v144, v144, v146
	v_sub_f32_e32 v146, v144, v145
	v_cmp_lt_f32_e32 vcc, s25, v146
	s_cbranch_vccz .LBB0_522
	v_max_f32_e32 v144, v144, v144
	v_max_f32_e32 v146, v145, v145
	v_max_f32_e32 v144, v146, v144
	v_sub_f32_e32 v145, v145, v144
	v_mul_f32_e32 v145, 0x3fb8aa3b, v145
	v_exp_f32_e32 v146, v145
	v_mov_b32_e32 v145, v144
	v_pk_mul_f32 v[32:33], v[32:33], v[146:147] op_sel_hi:[1,0]
	v_pk_mul_f32 v[30:31], v[30:31], v[146:147] op_sel_hi:[1,0]
	v_pk_mul_f32 v[28:29], v[28:29], v[146:147] op_sel_hi:[1,0]
	v_pk_mul_f32 v[26:27], v[26:27], v[146:147] op_sel_hi:[1,0]
	v_pk_mul_f32 v[24:25], v[24:25], v[146:147] op_sel_hi:[1,0]
	v_pk_mul_f32 v[22:23], v[22:23], v[146:147] op_sel_hi:[1,0]
	v_pk_mul_f32 v[20:21], v[20:21], v[146:147] op_sel_hi:[1,0]
	v_pk_mul_f32 v[18:19], v[18:19], v[146:147] op_sel_hi:[1,0]
	v_pk_mul_f32 v[16:17], v[16:17], v[146:147] op_sel_hi:[1,0]
	v_pk_mul_f32 v[14:15], v[14:15], v[146:147] op_sel_hi:[1,0]
	v_pk_mul_f32 v[12:13], v[12:13], v[146:147] op_sel_hi:[1,0]
	v_pk_mul_f32 v[10:11], v[10:11], v[146:147] op_sel_hi:[1,0]
	v_pk_mul_f32 v[8:9], v[8:9], v[146:147] op_sel_hi:[1,0]
	v_pk_mul_f32 v[6:7], v[6:7], v[146:147] op_sel_hi:[1,0]
	v_pk_mul_f32 v[4:5], v[4:5], v[146:147] op_sel_hi:[1,0]
	v_pk_mul_f32 v[2:3], v[2:3], v[146:147] op_sel_hi:[1,0]
	s_branch .LBB0_523

; DI f32x16 mfma32(bf16x8 a, bf16x8 b, f32x16 c) { return __builtin_amdgcn_mfma_f32_32x32x16_bf16(a, b, c, 0, 0, 0); }
; template <int NB>
; DI void softmax_pv(f32x16 (&s)[2], float& mrun, float& lsum, f32x16 (&O)[2], unsigned vaddr) {
;     ...
;   if (NB == 2) {
; #pragma unroll
;     for (int kb = 0; kb < 2; ++kb) {
; #pragma unroll
;       for (int e = 0; e < 16; e += 2) {
;         f32x2 t = {s[kb][e], s[kb][e + 1]};
;         t = t * l2e2 - mb2;
;         f32x2 pv;
;         pv[0] = __builtin_amdgcn_exp2f(t[0]);
;         pv[1] = __builtin_amdgcn_exp2f(t[1]);
;         s[kb][e] = pv[0];
;         s[kb][e + 1] = pv[1];
;         ps2 += pv;
;       }
;       u32x4 pp[2];
; #pragma unroll
;       for (int st = 0; st < 2; ++st)
; #pragma unroll
;         for (int j = 0; j < 4; ++j) pp[st][j] = pk_bf16(s[kb][8 * st + 2 * j], s[kb][8 * st + 2 * j + 1]);
;       __builtin_amdgcn_sched_barrier(0);
;       __builtin_amdgcn_s_setprio(1);
; #pragma unroll
;       for (int st = 0; st < 2; ++st) {
;         const bf16x8 pf = as_bf16x8(pp[st]);
; #pragma unroll
;         for (int db = 0; db < 2; ++db) {
;           const int ix = ((kb * 2 + st) * 2 + db) * 2;
;           u32x4 av;
;           av[0] = vf[ix][0]; av[1] = vf[ix][1]; av[2] = vf[ix + 1][0]; av[3] = vf[ix + 1][1];
;           O[db] = mfma32(as_bf16x8(av), pf, O[db]);
;         }
;       }
;       __builtin_amdgcn_s_setprio(0);
;       __builtin_amdgcn_sched_barrier(0);
;     }
;     ...
;   lsum = lsum * alpha + (ps2[0] + ps2[1]);
.LBB0_523:
	v_mul_f32_e32 v144, 0x3fb8aa3b, v145
	v_fma_f32 v66, v66, s28, -v144
	v_fma_f32 v67, v67, s28, -v144
	s_add_i32 s7, s7, 1
	v_exp_f32_e32 v150, v66
	v_exp_f32_e32 v151, v67
	v_fma_f32 v66, v68, s28, -v144
	v_fma_f32 v67, v69, s28, -v144
	s_nop 0
	v_exp_f32_e32 v152, v66
	v_exp_f32_e32 v153, v67
	v_fma_f32 v66, v70, s28, -v144
	v_fma_f32 v67, v71, s28, -v144
	s_nop 0
	v_exp_f32_e32 v154, v66
	v_exp_f32_e32 v155, v67
	v_fma_f32 v66, v72, s28, -v144
	v_fma_f32 v67, v73, s28, -v144
	v_cvt_pk_bf16_f32 v68, v154, v155
	v_exp_f32_e32 v156, v66
	v_exp_f32_e32 v157, v67
	v_fma_f32 v66, v74, s28, -v144
	v_fma_f32 v67, v75, s28, -v144
	v_cvt_pk_bf16_f32 v69, v156, v157
	v_exp_f32_e32 v74, v66
	v_exp_f32_e32 v75, v67
	v_fma_f32 v66, v76, s28, -v144
	v_fma_f32 v67, v77, s28, -v144
	v_cvt_pk_bf16_f32 v70, v74, v75
	v_exp_f32_e32 v76, v66
	v_exp_f32_e32 v77, v67
	v_fma_f32 v66, v78, s28, -v144
	v_fma_f32 v67, v79, s28, -v144
	v_cvt_pk_bf16_f32 v71, v76, v77
	v_exp_f32_e32 v78, v66
	v_exp_f32_e32 v79, v67
	v_fma_f32 v66, v80, s28, -v144
	v_fma_f32 v67, v81, s28, -v144
	v_cvt_pk_bf16_f32 v72, v78, v79
	v_exp_f32_e32 v80, v66
	v_exp_f32_e32 v81, v67
	v_cvt_pk_bf16_f32 v66, v150, v151
	v_cvt_pk_bf16_f32 v67, v152, v153
	v_cvt_pk_bf16_f32 v73, v80, v81
	s_waitcnt lgkmcnt(0)
	s_nop 0
	v_mfma_f32_32x32x16_bf16 v[18:33], v[134:137], v[66:69], v[18:33]
	v_mfma_f32_32x32x16_bf16 v[2:17], v[130:133], v[66:69], v[2:17]
	v_add_f32_e64 v66, v150, 0
	v_add_f32_e64 v67, v151, 0
	v_add_f32_e64 v66, v152, v66
	v_add_f32_e64 v67, v153, v67
	v_add_f32_e64 v66, v154, v66
	v_add_f32_e64 v67, v155, v67
	v_pk_add_f32 v[66:67], v[156:157], v[66:67]
	v_mfma_f32_32x32x16_bf16 v[18:33], v[126:129], v[70:73], v[18:33]
	v_add_f32_e64 v66, v74, v66
	v_add_f32_e64 v67, v75, v67
	v_add_f32_e64 v66, v76, v66
	v_add_f32_e64 v67, v77, v67
	v_add_f32_e64 v66, v78, v66
	v_add_f32_e64 v67, v79, v67
	v_pk_add_f32 v[66:67], v[80:81], v[66:67]
	v_mfma_f32_32x32x16_bf16 v[2:17], v[122:125], v[70:73], v[2:17]
	s_nop 0
	v_fma_f32 v50, v50, s28, -v144
	v_fma_f32 v51, v51, s28, -v144
	v_exp_f32_e32 v68, v50
	v_exp_f32_e32 v69, v51
	v_fma_f32 v50, v52, s28, -v144
	v_fma_f32 v51, v53, s28, -v144
	s_nop 0
	v_exp_f32_e32 v70, v50
	v_exp_f32_e32 v71, v51
	v_fma_f32 v50, v54, s28, -v144
	v_fma_f32 v51, v55, s28, -v144
	s_nop 0
	v_exp_f32_e32 v72, v50
	v_exp_f32_e32 v73, v51
	v_fma_f32 v50, v56, s28, -v144
	v_fma_f32 v51, v57, s28, -v144
	v_cvt_pk_bf16_f32 v52, v72, v73
	v_exp_f32_e32 v74, v50
	v_exp_f32_e32 v75, v51
	v_fma_f32 v50, v58, s28, -v144
	v_fma_f32 v51, v59, s28, -v144
	v_cvt_pk_bf16_f32 v53, v74, v75
	v_exp_f32_e32 v58, v50
	v_exp_f32_e32 v59, v51
	v_fma_f32 v50, v60, s28, -v144
	v_fma_f32 v51, v61, s28, -v144
	v_cvt_pk_bf16_f32 v54, v58, v59
	v_exp_f32_e32 v60, v50
	v_exp_f32_e32 v61, v51
	v_fma_f32 v50, v62, s28, -v144
	v_fma_f32 v51, v63, s28, -v144
	v_cvt_pk_bf16_f32 v55, v60, v61
	v_exp_f32_e32 v62, v50
	v_exp_f32_e32 v63, v51
	v_fma_f32 v50, v64, s28, -v144
	v_fma_f32 v51, v65, s28, -v144
	v_cvt_pk_bf16_f32 v56, v62, v63
	v_exp_f32_e32 v64, v50
	v_exp_f32_e32 v65, v51
	v_cvt_pk_bf16_f32 v50, v68, v69
	v_cvt_pk_bf16_f32 v51, v70, v71
	v_cvt_pk_bf16_f32 v57, v64, v65
	s_nop 0
	v_mfma_f32_32x32x16_bf16 v[18:33], v[118:121], v[50:53], v[18:33]
	v_mfma_f32_32x32x16_bf16 v[2:17], v[114:117], v[50:53], v[2:17]
	v_add_f32_e64 v50, v68, v66
	v_add_f32_e64 v51, v69, v67
	v_add_f32_e64 v50, v70, v50
	v_add_f32_e64 v51, v71, v51
	v_add_f32_e64 v50, v72, v50
	v_add_f32_e64 v51, v73, v51
	v_pk_add_f32 v[50:51], v[74:75], v[50:51]
	v_mfma_f32_32x32x16_bf16 v[18:33], v[110:113], v[54:57], v[18:33]
	v_add_f32_e64 v50, v58, v50
	v_add_f32_e64 v51, v59, v51
	v_add_f32_e64 v50, v60, v50
	v_add_f32_e64 v51, v61, v51
	v_add_f32_e64 v50, v62, v50
	v_add_f32_e64 v51, v63, v51
	v_pk_add_f32 v[50:51], v[64:65], v[50:51]
	v_mfma_f32_32x32x16_bf16 v[2:17], v[106:109], v[54:57], v[2:17]
	s_nop 0
	v_add_f32_e32 v106, v50, v51
	s_add_i32 s6, s6, 64
	s_cmp_eq_u32 s7, 35
	v_fmac_f32_e32 v106, v149, v146
	s_cbranch_scc1 .LBB0_525
	v_mov_b32_e32 v149, v106
	s_branch .LBB0_520
; template <int NB>
; DI void softmax_pv(f32x16 (&s)[2], float& mrun, float& lsum, f32x16 (&O)[2], unsigned vaddr) {
;     ...
;   if (NB == 2) tr_read_vtile(vf, vaddr);
;   else tr_read_vtile8(vf8, vaddr);
;   float mx = -1e30f;
; #pragma unroll
;   for (int kb = 0; kb < NB; ++kb)
; #pragma unroll
;     for (int e = 0; e < 16; ++e) mx = fmaxf(mx, s[kb][e]);
;   mx = xmax32(mx);
;   constexpr float THR = 8.f;
;   float alpha = 1.f;
;   if (__builtin_amdgcn_ballot_w64(mx - mrun > THR) != 0ull) {
;     const float mnew = fmaxf(mrun, mx);
;     alpha = __builtin_amdgcn_exp2f((mrun - mnew) * L2E);
;     mrun = mnew;
; #pragma unroll
; template <int kind>
; __device__ void attn_job(const Params& p, int layer, int idx, char* smem) {
;     ...
;     u16* Kb = Ks + (i & 1) * 64 * KS_STRIDE;
;     u16* Vb = Vt + (i & 1) * 64 * KS_STRIDE;
;     *(u32x4*)(Kb + lkey * KS_STRIDE + lc * 8) = kreg;
;     *(u32x4*)(Vb + lkey * KS_STRIDE + lc * 8) = vreg;
;     lds_barrier();
;     if (i + 1 < ntiles) {
;       const size_t ro = (size_t)(tile_row0(i + 1) + lkey) * ZW;
;       kreg = *(const u32x4*)(Z + ro + kcol + lc * 8);
;       vreg = *(const u32x4*)(Z + ro + vcol + lc * 8);
;     }
;     if (kind == 1 && i >= 4) {
;       const int kr = R0 + i - 4;
;       if (kr >= r0A && kr < r0A + 9) {
;         f32x16 s[2];
; #pragma unroll
;         for (int st = 0; st < 4; ++st) s[0] = mfma32(ld_frag16(Kb + (k0 + tq) * KS_STRIDE + 16 * st + 8 * hh), qf[st], st == 0 ? zero16 : s[0]);
;         const bool rowvalid = (kr >= r0l) && (kr < r0l + 8);
;         const unsigned m = rowvalid ? colmask : 0u;
;         const float* brow = rpbs + (kr - qrow_l + 7) * 32 + dcbase;
; #pragma unroll
;         for (int e = 0; e < 16; ++e) {
;           const float bias = brow[(e & 3) + 8 * (e >> 2)];
;           s[0][e] = ((m >> e) & 1u) ? s[0][e] + bias : -1e30f;
;         }
;         softmax_pv<1>(s, mrun, lsum, O, (unsigned)(size_t)Vb + vlane_off + (unsigned)(k0 * KS_STRIDE * 2));
;       }
;     } else {
;       f32x16 s[2];
;       __builtin_amdgcn_s_setprio(1);
; #pragma unroll
;       for (int kb = 0; kb < 2; ++kb) {
; #pragma unroll
;         for (int st = 0; st < 4; ++st) s[kb] = mfma32(ld_frag16(Kb + (kb * 32 + tq) * KS_STRIDE + 16 * st + 8 * hh), qf[st], st == 0 ? zero16 : s[kb]);
;       }
;       __builtin_amdgcn_s_setprio(0);
;       softmax_pv<2>(s, mrun, lsum, O, (unsigned)(size_t)Vb + vlane_off);
.LBB0_525:
	v_add3_u32 v0, 0, v148, v0
	s_waitcnt vmcnt(1)
	ds_write_b128 v0, v[98:101] offset:9216
	s_waitcnt vmcnt(0)
	ds_write_b128 v0, v[102:105] offset:27648
	s_waitcnt lgkmcnt(0)
	s_barrier
	s_nop 0
	v_add3_u32 v0, 0, v140, v143
	ds_read_b128 v[66:69], v0 offset:9216
	s_waitcnt lgkmcnt(0)
	v_mfma_f32_32x32x16_bf16 v[50:65], v[66:69], v[94:97], v[34:49]
	ds_read_b128 v[66:69], v0 offset:9248
	s_waitcnt lgkmcnt(0)
	v_mfma_f32_32x32x16_bf16 v[50:65], v[66:69], v[90:93], v[50:65]
	ds_read_b128 v[66:69], v0 offset:9280
	s_waitcnt lgkmcnt(0)
	v_mfma_f32_32x32x16_bf16 v[50:65], v[66:69], v[86:89], v[50:65]
	ds_read_b128 v[66:69], v0 offset:9312
	s_waitcnt lgkmcnt(0)
	v_mfma_f32_32x32x16_bf16 v[50:65], v[66:69], v[82:85], v[50:65]
	ds_read_b128 v[66:69], v0 offset:13824
	s_waitcnt lgkmcnt(0)
	v_mfma_f32_32x32x16_bf16 v[34:49], v[66:69], v[94:97], v[34:49]
	ds_read_b128 v[66:69], v0 offset:13856
	s_waitcnt lgkmcnt(0)
	v_mfma_f32_32x32x16_bf16 v[34:49], v[66:69], v[90:93], v[34:49]
	ds_read_b128 v[66:69], v0 offset:13888
	s_waitcnt lgkmcnt(0)
	v_mfma_f32_32x32x16_bf16 v[34:49], v[66:69], v[86:89], v[34:49]
	ds_read_b128 v[66:69], v0 offset:13920
	s_waitcnt lgkmcnt(0)
	v_mfma_f32_32x32x16_bf16 v[34:49], v[66:69], v[82:85], v[34:49]
	s_nop 0
	s_add_i32 s2, 0, 0x6c00
	s_cmp_lg_u32 s2, -1
	s_cselect_b32 s2, s2, 0
	v_add_u32_e32 v0, s2, v141
	ds_read_b64_tr_b16 v[94:95], v0 offset:0
	ds_read_b64_tr_b16 v[96:97], v0 offset:1152
	ds_read_b64_tr_b16 v[90:91], v0 offset:64
	ds_read_b64_tr_b16 v[92:93], v0 offset:1216
	ds_read_b64_tr_b16 v[86:87], v0 offset:2304
	ds_read_b64_tr_b16 v[88:89], v0 offset:3456
	ds_read_b64_tr_b16 v[82:83], v0 offset:2368
	ds_read_b64_tr_b16 v[84:85], v0 offset:3520
	ds_read_b64_tr_b16 v[78:79], v0 offset:4608
	ds_read_b64_tr_b16 v[80:81], v0 offset:5760
	ds_read_b64_tr_b16 v[74:75], v0 offset:4672
	ds_read_b64_tr_b16 v[76:77], v0 offset:5824
	ds_read_b64_tr_b16 v[70:71], v0 offset:6912
	ds_read_b64_tr_b16 v[72:73], v0 offset:8064
	ds_read_b64_tr_b16 v[66:67], v0 offset:6976
	ds_read_b64_tr_b16 v[68:69], v0 offset:8128
	s_waitcnt lgkmcnt(0)
	v_max3_f32 v0, v50, s24, v51
	v_max3_f32 v0, v0, v52, v53
	v_max3_f32 v0, v0, v54, v55
	v_max3_f32 v0, v0, v56, v57
	v_max3_f32 v0, v0, v58, v59
	v_max3_f32 v0, v0, v60, v61
	v_max3_f32 v0, v0, v62, v63
	v_max3_f32 v0, v0, v64, v65
	v_max3_f32 v0, v0, v34, v35
	v_max3_f32 v0, v0, v36, v37
	v_max3_f32 v0, v0, v38, v39
	v_max3_f32 v0, v0, v40, v41
	v_max3_f32 v0, v0, v42, v43
	v_max3_f32 v0, v0, v44, v45
	v_max3_f32 v0, v0, v46, v47
	v_max3_f32 v0, v0, v48, v49
	v_mov_b32_e32 v98, v0
	s_nop 1
	v_permlane32_swap_b32_e32 v0, v98
	v_max_f32_e32 v98, v98, v98
	v_max_f32_e32 v0, v0, v0
	v_max_f32_e32 v0, v0, v98
	v_sub_f32_e32 v98, v0, v145
	v_cmp_lt_f32_e32 vcc, s25, v98
	s_cbranch_vccz .LBB0_527
	v_max_f32_e32 v0, v0, v0
	v_max_f32_e32 v98, v145, v145
	v_max_f32_e32 v98, v98, v0
	v_sub_f32_e32 v0, v145, v98
	v_mul_f32_e32 v0, 0x3fb8aa3b, v0
	v_exp_f32_e32 v0, v0
	v_mul_f32_e32 v144, 0x3fb8aa3b, v98
	v_pk_mul_f32 v[32:33], v[32:33], v[0:1] op_sel_hi:[1,0]
	v_pk_mul_f32 v[30:31], v[30:31], v[0:1] op_sel_hi:[1,0]
	v_pk_mul_f32 v[28:29], v[28:29], v[0:1] op_sel_hi:[1,0]
	v_pk_mul_f32 v[26:27], v[26:27], v[0:1] op_sel_hi:[1,0]
	v_pk_mul_f32 v[24:25], v[24:25], v[0:1] op_sel_hi:[1,0]
	v_pk_mul_f32 v[22:23], v[22:23], v[0:1] op_sel_hi:[1,0]
	v_pk_mul_f32 v[20:21], v[20:21], v[0:1] op_sel_hi:[1,0]
	v_pk_mul_f32 v[18:19], v[18:19], v[0:1] op_sel_hi:[1,0]
	v_pk_mul_f32 v[16:17], v[16:17], v[0:1] op_sel_hi:[1,0]
	v_pk_mul_f32 v[14:15], v[14:15], v[0:1] op_sel_hi:[1,0]
	v_pk_mul_f32 v[12:13], v[12:13], v[0:1] op_sel_hi:[1,0]
	v_pk_mul_f32 v[10:11], v[10:11], v[0:1] op_sel_hi:[1,0]
	v_pk_mul_f32 v[8:9], v[8:9], v[0:1] op_sel_hi:[1,0]
	v_pk_mul_f32 v[6:7], v[6:7], v[0:1] op_sel_hi:[1,0]
	v_pk_mul_f32 v[4:5], v[4:5], v[0:1] op_sel_hi:[1,0]
	v_pk_mul_f32 v[2:3], v[2:3], v[0:1] op_sel_hi:[1,0]
	s_branch .LBB0_528

; DI f32x16 mfma32(bf16x8 a, bf16x8 b, f32x16 c) { return __builtin_amdgcn_mfma_f32_32x32x16_bf16(a, b, c, 0, 0, 0); }
; template <int NB>
; DI void softmax_pv(f32x16 (&s)[2], float& mrun, float& lsum, f32x16 (&O)[2], unsigned vaddr) {
;     ...
;   if (NB == 2) {
; #pragma unroll
;     for (int kb = 0; kb < 2; ++kb) {
; #pragma unroll
;       for (int e = 0; e < 16; e += 2) {
;         f32x2 t = {s[kb][e], s[kb][e + 1]};
;         t = t * l2e2 - mb2;
;         f32x2 pv;
;         pv[0] = __builtin_amdgcn_exp2f(t[0]);
;         pv[1] = __builtin_amdgcn_exp2f(t[1]);
;         s[kb][e] = pv[0];
;         s[kb][e + 1] = pv[1];
;         ps2 += pv;
;       }
;       u32x4 pp[2];
; #pragma unroll
;       for (int st = 0; st < 2; ++st)
; #pragma unroll
;         for (int j = 0; j < 4; ++j) pp[st][j] = pk_bf16(s[kb][8 * st + 2 * j], s[kb][8 * st + 2 * j + 1]);
;       __builtin_amdgcn_sched_barrier(0);
;       __builtin_amdgcn_s_setprio(1);
; #pragma unroll
;       for (int st = 0; st < 2; ++st) {
;         const bf16x8 pf = as_bf16x8(pp[st]);
; #pragma unroll
;         for (int db = 0; db < 2; ++db) {
;           const int ix = ((kb * 2 + st) * 2 + db) * 2;
;           u32x4 av;
;           av[0] = vf[ix][0]; av[1] = vf[ix][1]; av[2] = vf[ix + 1][0]; av[3] = vf[ix + 1][1];
;           O[db] = mfma32(as_bf16x8(av), pf, O[db]);
;         }
;       }
;       __builtin_amdgcn_s_setprio(0);
;       __builtin_amdgcn_sched_barrier(0);
.LBB0_528:
	v_mov_b32_e32 v145, v144
	v_pk_fma_f32 v[50:51], v[50:51], s[28:29], v[144:145] op_sel_hi:[1,0,1] neg_lo:[0,0,1] neg_hi:[0,0,1]
	s_nop 0
	v_exp_f32_e32 v98, v50
	v_exp_f32_e32 v99, v51
	v_pk_fma_f32 v[50:51], v[52:53], s[28:29], v[144:145] op_sel_hi:[1,0,1] neg_lo:[0,0,1] neg_hi:[0,0,1]
	s_nop 0
	v_exp_f32_e32 v100, v50
	v_exp_f32_e32 v101, v51
	v_pk_fma_f32 v[50:51], v[54:55], s[28:29], v[144:145] op_sel_hi:[1,0,1] neg_lo:[0,0,1] neg_hi:[0,0,1]
	s_nop 0
	v_exp_f32_e32 v102, v50
	v_exp_f32_e32 v103, v51
	v_pk_fma_f32 v[50:51], v[56:57], s[28:29], v[144:145] op_sel_hi:[1,0,1] neg_lo:[0,0,1] neg_hi:[0,0,1]
	v_cvt_pk_bf16_f32 v52, v102, v103
	v_exp_f32_e32 v104, v50
	v_exp_f32_e32 v105, v51
	v_pk_fma_f32 v[50:51], v[58:59], s[28:29], v[144:145] op_sel_hi:[1,0,1] neg_lo:[0,0,1] neg_hi:[0,0,1]
	v_cvt_pk_bf16_f32 v53, v104, v105
	v_exp_f32_e32 v58, v50
	v_exp_f32_e32 v59, v51
	v_pk_fma_f32 v[50:51], v[60:61], s[28:29], v[144:145] op_sel_hi:[1,0,1] neg_lo:[0,0,1] neg_hi:[0,0,1]
	v_cvt_pk_bf16_f32 v54, v58, v59
	v_exp_f32_e32 v60, v50
	v_exp_f32_e32 v61, v51
	v_pk_fma_f32 v[50:51], v[62:63], s[28:29], v[144:145] op_sel_hi:[1,0,1] neg_lo:[0,0,1] neg_hi:[0,0,1]
	v_cvt_pk_bf16_f32 v55, v60, v61
	v_exp_f32_e32 v62, v50
	v_exp_f32_e32 v63, v51
	v_pk_fma_f32 v[50:51], v[64:65], s[28:29], v[144:145] op_sel_hi:[1,0,1] neg_lo:[0,0,1] neg_hi:[0,0,1]
	v_cvt_pk_bf16_f32 v56, v62, v63
	v_exp_f32_e32 v64, v50
	v_exp_f32_e32 v65, v51
	v_cvt_pk_bf16_f32 v50, v98, v99
	v_cvt_pk_bf16_f32 v51, v100, v101
	v_cvt_pk_bf16_f32 v57, v64, v65
	s_nop 0
	v_mfma_f32_32x32x16_bf16 v[18:33], v[94:97], v[50:53], v[18:33]
	v_mfma_f32_32x32x16_bf16 v[2:17], v[90:93], v[50:53], v[2:17]
	v_add_f32_e64 v50, v98, 0
	v_add_f32_e64 v51, v99, 0
	v_add_f32_e64 v50, v100, v50
	v_add_f32_e64 v51, v101, v51
	v_add_f32_e64 v50, v102, v50
	v_add_f32_e64 v51, v103, v51
	v_pk_add_f32 v[50:51], v[104:105], v[50:51]
	v_mfma_f32_32x32x16_bf16 v[18:33], v[86:89], v[54:57], v[18:33]
	v_add_f32_e64 v50, v58, v50
	v_add_f32_e64 v51, v59, v51
	v_add_f32_e64 v50, v60, v50
	v_add_f32_e64 v51, v61, v51
	v_add_f32_e64 v50, v62, v50
	v_add_f32_e64 v51, v63, v51
	v_pk_add_f32 v[50:51], v[64:65], v[50:51]
	v_mfma_f32_32x32x16_bf16 v[2:17], v[82:85], v[54:57], v[2:17]
	s_nop 0
	v_fma_f32 v34, v34, s28, -v144
	v_fma_f32 v35, v35, s28, -v145
	v_exp_f32_e32 v52, v34
	v_exp_f32_e32 v53, v35
	v_pk_fma_f32 v[34:35], v[36:37], s[28:29], v[144:145] op_sel_hi:[1,0,1] neg_lo:[0,0,1] neg_hi:[0,0,1]
	s_nop 0
	v_exp_f32_e32 v54, v34
	v_exp_f32_e32 v55, v35
	v_pk_fma_f32 v[34:35], v[38:39], s[28:29], v[144:145] op_sel_hi:[1,0,1] neg_lo:[0,0,1] neg_hi:[0,0,1]
	s_nop 0
	v_exp_f32_e32 v56, v34
	v_exp_f32_e32 v57, v35
	v_pk_fma_f32 v[34:35], v[40:41], s[28:29], v[144:145] op_sel_hi:[1,0,1] neg_lo:[0,0,1] neg_hi:[0,0,1]
	v_cvt_pk_bf16_f32 v36, v56, v57
	v_exp_f32_e32 v58, v34
	v_exp_f32_e32 v59, v35
	v_pk_fma_f32 v[34:35], v[42:43], s[28:29], v[144:145] op_sel_hi:[1,0,1] neg_lo:[0,0,1] neg_hi:[0,0,1]
	v_cvt_pk_bf16_f32 v37, v58, v59
	v_exp_f32_e32 v42, v34
	v_exp_f32_e32 v43, v35
	v_pk_fma_f32 v[34:35], v[44:45], s[28:29], v[144:145] op_sel_hi:[1,0,1] neg_lo:[0,0,1] neg_hi:[0,0,1]
	v_cvt_pk_bf16_f32 v38, v42, v43
	v_exp_f32_e32 v44, v34
	v_exp_f32_e32 v45, v35
	v_pk_fma_f32 v[34:35], v[46:47], s[28:29], v[144:145] op_sel_hi:[1,0,1] neg_lo:[0,0,1] neg_hi:[0,0,1]
	v_cvt_pk_bf16_f32 v39, v44, v45
	v_exp_f32_e32 v46, v34
	v_exp_f32_e32 v47, v35
	v_pk_fma_f32 v[34:35], v[48:49], s[28:29], v[144:145] op_sel_hi:[1,0,1] neg_lo:[0,0,1] neg_hi:[0,0,1]
; DI f32x16 mfma32(bf16x8 a, bf16x8 b, f32x16 c) { return __builtin_amdgcn_mfma_f32_32x32x16_bf16(a, b, c, 0, 0, 0); }
; DI float xsum32(float x) { auto r = __builtin_amdgcn_permlane32_swap(__float_as_uint(x), __float_as_uint(x), false, false); return __uint_as_float(r[0]) + __uint_as_float(r[1]); }
; template <int NB>
; DI void softmax_pv(f32x16 (&s)[2], float& mrun, float& lsum, f32x16 (&O)[2], unsigned vaddr) {
;     ...
; #pragma unroll
;       for (int st = 0; st < 2; ++st) {
;         const bf16x8 pf = as_bf16x8(pp[st]);
; #pragma unroll
;         for (int db = 0; db < 2; ++db) {
;           const int ix = ((kb * 2 + st) * 2 + db) * 2;
;           u32x4 av;
;           av[0] = vf[ix][0]; av[1] = vf[ix][1]; av[2] = vf[ix + 1][0]; av[3] = vf[ix + 1][1];
;           O[db] = mfma32(as_bf16x8(av), pf, O[db]);
;         }
;       }
;       __builtin_amdgcn_s_setprio(0);
;       __builtin_amdgcn_sched_barrier(0);
; template <int kind>
; __device__ void attn_job(const Params& p, int layer, int idx, char* smem) {
;     ...
;   lsum = xsum32(lsum);
;   const float inv = 1.f / lsum;
;   u16* dst = p.xn + (size_t)qtok * DM + ocol;
; #pragma unroll
;   for (int db = 0; db < 2; ++db)
; #pragma unroll
;     for (int k = 0; k < 2; ++k) {
;       const int gA = 2 * k, gB = 2 * k + 1;
;       const unsigned x0 = pk_bf16(O[db][4 * gA + 0] * inv, O[db][4 * gA + 1] * inv), x1 = pk_bf16(O[db][4 * gA + 2] * inv, O[db][4 * gA + 3] * inv);
;       const unsigned y0 = pk_bf16(O[db][4 * gB + 0] * inv, O[db][4 * gB + 1] * inv), y1 = pk_bf16(O[db][4 * gB + 2] * inv, O[db][4 * gB + 3] * inv);
;       auto r0 = __builtin_amdgcn_permlane32_swap(x0, y0, false, false);
;       auto r1 = __builtin_amdgcn_permlane32_swap(x1, y1, false, false);
;       u32x4 wv;
;       wv[0] = r0[0]; wv[1] = r1[0]; wv[2] = r0[1]; wv[3] = r1[1];
;       *(u32x4*)(dst + db * 32 + 16 * k + 8 * hh) = wv;
;     }
;   __syncthreads();
	v_cvt_pk_bf16_f32 v40, v46, v47
	v_exp_f32_e32 v48, v34
	v_exp_f32_e32 v49, v35
	v_cvt_pk_bf16_f32 v34, v52, v53
	v_cvt_pk_bf16_f32 v35, v54, v55
	v_cvt_pk_bf16_f32 v41, v48, v49
	s_nop 0
	v_mfma_f32_32x32x16_bf16 v[18:33], v[78:81], v[34:37], v[18:33]
	v_mfma_f32_32x32x16_bf16 v[2:17], v[74:77], v[34:37], v[2:17]
	v_add_f32_e64 v34, v52, v50
	v_add_f32_e64 v35, v53, v51
	v_add_f32_e64 v34, v54, v34
	v_add_f32_e64 v35, v55, v35
	v_add_f32_e64 v34, v56, v34
	v_add_f32_e64 v35, v57, v35
	v_pk_add_f32 v[34:35], v[58:59], v[34:35]
	v_mfma_f32_32x32x16_bf16 v[18:33], v[70:73], v[38:41], v[18:33]
	v_add_f32_e64 v34, v42, v34
	v_add_f32_e64 v35, v43, v35
	v_add_f32_e64 v34, v44, v34
	v_add_f32_e64 v35, v45, v35
	v_add_f32_e64 v34, v46, v34
	v_add_f32_e64 v35, v47, v35
	v_pk_add_f32 v[34:35], v[48:49], v[34:35]
	v_mfma_f32_32x32x16_bf16 v[2:17], v[66:69], v[38:41], v[2:17]
	s_nop 0
	v_add_f32_e32 v34, v34, v35
	v_fmac_f32_e32 v34, v106, v0
	v_mov_b32_e32 v0, v34
	s_nop 1
	v_permlane32_swap_b32_e32 v34, v0
	v_add_f32_e32 v0, v34, v0
	v_div_scale_f32 v34, s[2:3], v0, v0, 1.0
	v_rcp_f32_e32 v35, v34
	s_nop 0
	v_fma_f32 v36, -v34, v35, 1.0
	v_fmac_f32_e32 v35, v36, v35
	v_div_scale_f32 v36, vcc, 1.0, v0, 1.0
	v_mul_f32_e32 v37, v36, v35
	v_fma_f32 v38, -v34, v37, v36
	v_fmac_f32_e32 v37, v38, v35
	v_fma_f32 v34, -v34, v37, v36
	v_div_fmas_f32 v34, v34, v35, v37
	v_div_fixup_f32 v34, v34, v0, 1.0
	v_lshlrev_b32_e32 v0, 11, v139
	v_pk_mul_f32 v[18:19], v[18:19], v[34:35] op_sel_hi:[1,0]
	v_pk_mul_f32 v[20:21], v[20:21], v[34:35] op_sel_hi:[1,0]
	v_pk_mul_f32 v[2:3], v[2:3], v[34:35] op_sel_hi:[1,0]
	v_pk_mul_f32 v[4:5], v[4:5], v[34:35] op_sel_hi:[1,0]
	v_lshl_add_u64 v[36:37], s[54:55], 0, v[0:1]
	v_cvt_pk_bf16_f32 v18, v18, v19
	v_cvt_pk_bf16_f32 v19, v20, v21
	v_pk_mul_f32 v[20:21], v[22:23], v[34:35] op_sel_hi:[1,0]
	v_pk_mul_f32 v[22:23], v[24:25], v[34:35] op_sel_hi:[1,0]
	v_cvt_pk_bf16_f32 v2, v2, v3
	v_cvt_pk_bf16_f32 v3, v4, v5
	v_pk_mul_f32 v[4:5], v[6:7], v[34:35] op_sel_hi:[1,0]
	v_pk_mul_f32 v[6:7], v[8:9], v[34:35] op_sel_hi:[1,0]
	v_lshl_add_u64 v[36:37], s[0:1], 1, v[36:37]
	v_lshlrev_b32_e32 v0, 1, v138
	v_cvt_pk_bf16_f32 v20, v20, v21
	v_cvt_pk_bf16_f32 v21, v22, v23
	v_cvt_pk_bf16_f32 v4, v4, v5
	v_cvt_pk_bf16_f32 v5, v6, v7
	v_lshl_add_u64 v[36:37], v[36:37], 0, v[0:1]
	v_permlane32_swap_b32_e32 v18, v20
	v_permlane32_swap_b32_e32 v19, v21
	v_permlane32_swap_b32_e32 v2, v4
	v_permlane32_swap_b32_e32 v3, v5
	global_store_dwordx4 v[36:37], v[18:21], off offset:1024
	global_store_dwordx4 v[36:37], v[2:5], off offset:1088
	v_pk_mul_f32 v[22:23], v[32:33], v[34:35] op_sel_hi:[1,0]
	v_pk_mul_f32 v[18:19], v[26:27], v[34:35] op_sel_hi:[1,0]
	v_pk_mul_f32 v[20:21], v[28:29], v[34:35] op_sel_hi:[1,0]
	v_pk_mul_f32 v[2:3], v[10:11], v[34:35] op_sel_hi:[1,0]
	v_pk_mul_f32 v[4:5], v[12:13], v[34:35] op_sel_hi:[1,0]
	v_cvt_pk_bf16_f32 v18, v18, v19
	v_cvt_pk_bf16_f32 v19, v20, v21
	v_pk_mul_f32 v[20:21], v[30:31], v[34:35] op_sel_hi:[1,0]
	v_cvt_pk_bf16_f32 v2, v2, v3
	v_cvt_pk_bf16_f32 v3, v4, v5
	v_pk_mul_f32 v[4:5], v[14:15], v[34:35] op_sel_hi:[1,0]
	v_pk_mul_f32 v[6:7], v[16:17], v[34:35] op_sel_hi:[1,0]
	v_cvt_pk_bf16_f32 v20, v20, v21
	v_cvt_pk_bf16_f32 v21, v22, v23
	v_cvt_pk_bf16_f32 v4, v4, v5
	v_cvt_pk_bf16_f32 v5, v6, v7
	v_permlane32_swap_b32_e32 v18, v20
	v_permlane32_swap_b32_e32 v19, v21
	v_permlane32_swap_b32_e32 v2, v4
	v_permlane32_swap_b32_e32 v3, v5
	global_store_dwordx4 v[36:37], v[18:21], off offset:1056
	global_store_dwordx4 v[36:37], v[2:5], off offset:1120
	s_barrier
